# adds two-queue P4: half the WGs draw sample-attention tasks, the other half start on prompt attention/conv units
# speedup vs baseline: 1.0236x; 1.0015x over previous
; #define LAS __attribute__((address_space(3)))
; __device__ __forceinline__ unsigned grab(unsigned* ctr, volatile LAS unsigned* misc, int& it, int tid) {
;     if (tid == 0) misc[20 + (it & 1)] = __hip_atomic_fetch_add(ctr, 1u, __ATOMIC_RELAXED, __HIP_MEMORY_SCOPE_AGENT);
;     __syncthreads();
; __global__ void __launch_bounds__(512, 2) mk_fwd(Args args) {
;     ...
;     if (IN(4)) {
;         int it = 0; unsigned id = grab(fctl + 64 * 20, MISC, it, tid);
.LBB0_1011:
	s_cmp_lt_i32 s82, 5
	s_cselect_b64 s[2:3], -1, 0
	s_add_u32 s4, s80, 0x1aafb100
	s_addc_u32 s5, s81, 0
	v_writelane_b32 v250, s4, 14
	s_nop 1
	v_writelane_b32 v250, s5, 15
	s_add_u32 s4, s80, 0x1bb7b100
	s_addc_u32 s5, s81, 0
	v_writelane_b32 v250, s4, 16
	s_nop 1
	v_writelane_b32 v250, s5, 17
	s_add_u32 s4, s80, 0x1d43b100
	s_addc_u32 s5, s81, 0
	v_writelane_b32 v250, s4, 26
	s_and_b64 s[0:1], s[2:3], s[0:1]
	s_nop 0
	v_writelane_b32 v250, s5, 27
	v_writelane_b32 v250, s0, 28
	s_andn2_b64 vcc, exec, s[0:1]
	s_nop 0
	v_writelane_b32 v250, s1, 29
	s_cbranch_vccnz .LBB0_1209
	s_bitcmp1_b32 s96, 3
	s_movk_i32 s99, 0
	s_cselect_b32 s99, 0x180, s99
	s_movk_i32 s100, 0x5400
	s_cselect_b32 s100, 0x5500, s100
	s_add_u32 s0, s80, s100
	s_addc_u32 s1, s81, 0
	v_writelane_b32 v250, s0, 18
	v_cmp_eq_u32_e64 s[6:7], 0, v0
	s_nop 0
	v_writelane_b32 v250, s1, 19
	s_and_saveexec_b64 s[0:1], s[6:7]
	s_cbranch_execz .LBB0_1016
	s_mov_b64 s[4:5], exec
	s_waitcnt vmcnt(0)
	v_mbcnt_lo_u32_b32 v2, s4, 0
	v_mbcnt_hi_u32_b32 v2, s5, v2
	v_cmp_eq_u32_e32 vcc, 0, v2
	s_and_saveexec_b64 s[2:3], vcc
	s_cbranch_execz .LBB0_1015
	s_bcnt1_i32_b64 s4, s[4:5]
	v_mov_b32_e32 v4, s4
	v_readlane_b32 s4, v250, 18
	s_waitcnt lgkmcnt(0)
	v_mov_b32_e32 v3, 0
	v_readlane_b32 s5, v250, 19
	s_nop 4
	global_atomic_add v3, v3, v4, s[4:5] sc0

; #define LAS __attribute__((address_space(3)))
; __device__ __forceinline__ void attn_sample_g12(const Args& a, LAS unsigned char* lds, const bf16* Q, const bf16* Kb, const bf16* Vb, bf16* OG, float* ML, int b, int g, int tid) {
;     const int w = tid >> 6, lane = tid & 63, s = w >> 1, half = w & 1;
;     const int W = 128 << (2 * g), d = 1 << (2 * g);
;     const char* ck = (const char*)(a.in[2 + 2 * g] + (size_t)b * W * 256); const char* cv = (const char*)(a.in[3 + 2 * g] + (size_t)b * W * 256); const unsigned voff = (unsigned)lane * 16u;
;     const size_t row = (size_t)TP + b * 4 + s; const int head = lane >> 4, dl = (lane & 15) * 4;
;     const int hcol = (4 * g + head) * 64 + dl;
;     float q[4]; { const v2u qw = *(const v2u*)(Q + row * 768 + hcol); q[0] = bfl(qw.x); q[1] = bfh(qw.x); q[2] = bfl(qw.y); q[3] = bfh(qw.y); }
;     float m = -INFINITY, l = 0.f, o[4] = {0.f, 0.f, 0.f, 0.f};
;     const int jbeg = half * 65, jend = half ? 129 : 65;
; __global__ void __launch_bounds__(512, 2) mk_fwd(Args args) {
;     ...
;         int it = 0; unsigned id = grab(fctl + 64 * 20, MISC, it, tid);
;         while (id < 384u) { attn_sample_g12(args, lds, Qb, Kb, Vb, OG, ML, (int)(id / 3u), (int)(id % 3u), tid); id = grab(fctl + 64 * 20, MISC, it, tid); }
.LBB0_1016:
	s_or_b64 exec, exec, s[0:1]
	s_add_u32 s4, s80, 0x1377b100
	s_addc_u32 s5, s81, 0
	s_add_u32 s88, s80, 0x1503b100
	s_addc_u32 s89, s81, 0
	s_add_i32 s0, 0, 0x20050
	s_waitcnt vmcnt(0)
	v_mov_b32_e32 v2, s0
	s_waitcnt lgkmcnt(0)
	s_barrier
	ds_read_b32 v2, v2
	s_mov_b32 s1, 0
	s_mov_b32 s33, 1
	s_waitcnt lgkmcnt(0)
	v_readfirstlane_b32 s17, v2
	s_add_u32 s17, s17, s99
	s_cmpk_gt_u32 s17, 0x17f
	s_cbranch_scc1 .LBB0_1096
	v_bfe_u32 v2, v0, 6, 1
	v_bfe_u32 v4, v0, 4, 2
	v_and_b32_e32 v3, 64, v0
	v_readlane_b32 s2, v250, 16
	v_and_b32_e32 v5, 15, v0
	v_mul_u32_u24_e32 v157, 0x41, v2
	v_cmp_ne_u32_e64 s[8:9], 0, v3
	v_mov_b32_e32 v3, 0x81
	v_mov_b32_e32 v7, 0x41
	v_cmp_eq_u32_e64 s[10:11], 0, v2
	v_mov_b32_e32 v133, 0
	v_or_b32_e32 v2, 64, v0
	v_lshlrev_b32_e32 v132, 7, v4
	v_readlane_b32 s3, v250, 17
	v_lshlrev_b32_e32 v6, 2, v5
	v_cndmask_b32_e64 v158, v3, v7, s[10:11]
	v_mul_u32_u24_e32 v8, 24, v2
	v_lshl_add_u64 v[2:3], s[2:3], 0, v[132:133]
	v_lshlrev_b32_e32 v132, 3, v5
	v_lshl_add_u64 v[134:135], v[2:3], 0, v[132:133]
	v_lshl_or_b32 v2, v4, 6, v6
	v_lshlrev_b32_e32 v159, 1, v2
	v_mbcnt_lo_u32_b32 v2, -1, 0
	v_readlane_b32 s2, v250, 26
	v_mbcnt_hi_u32_b32 v163, -1, v2
	v_mul_u32_u24_e32 v7, 24, v0
	v_lshlrev_b32_e32 v132, 3, v4
	v_readlane_b32 s3, v250, 27
	v_and_b32_e32 v2, 64, v163
	v_lshrrev_b32_e32 v156, 7, v0
	v_cmp_lt_u32_e64 s[12:13], v157, v158
	v_lshlrev_b32_e32 v130, 4, v162
	v_mov_b32_e32 v131, v133
	v_cmp_eq_u32_e64 s[14:15], 0, v5
	v_lshl_add_u64 v[136:137], s[2:3], 0, v[132:133]
	s_movk_i32 s50, 0x600
	v_add_u32_e32 v160, 0, v7
	v_add_u32_e32 v161, 0, v8
	s_movk_i32 s51, 0x7fff
	v_xor_b32_e32 v164, 1, v163
	v_add_u32_e32 v165, 64, v2
	v_xor_b32_e32 v166, 2, v163
	v_xor_b32_e32 v167, 4, v163
	v_xor_b32_e32 v168, 8, v163
	v_mov_b32_e32 v169, 0xff800000
	v_mov_b32_e32 v170, 1
	s_branch .LBB0_1020

; #define LAS __attribute__((address_space(3)))
; __device__ __forceinline__ unsigned grab(unsigned* ctr, volatile LAS unsigned* misc, int& it, int tid) {
;     if (tid == 0) misc[20 + (it & 1)] = __hip_atomic_fetch_add(ctr, 1u, __ATOMIC_RELAXED, __HIP_MEMORY_SCOPE_AGENT);
;     __syncthreads();
;     const unsigned v = (unsigned)__builtin_amdgcn_readfirstlane((int)misc[20 + (it & 1)]); ++it; return v;
; }
; __global__ void __launch_bounds__(512, 2) mk_fwd(Args args) {
;     ...
;         while (id < 384u) { attn_sample_g12(args, lds, Qb, Kb, Vb, OG, ML, (int)(id / 3u), (int)(id % 3u), tid); id = grab(fctl + 64 * 20, MISC, it, tid); }
.LBB0_1019:
	s_or_b64 exec, exec, s[2:3]
	s_lshl_b32 s0, s0, 2
	s_add_i32 s0, s0, 0
	s_add_i32 s0, s0, 0x20050
	v_mov_b32_e32 v2, s0
	s_waitcnt lgkmcnt(0)
	s_barrier
	ds_read_b32 v2, v2
	s_add_i32 s33, s33, 1
	s_waitcnt lgkmcnt(0)
	v_readfirstlane_b32 s17, v2
	s_add_u32 s17, s17, s99
	s_cmpk_lt_u32 s17, 0x180
	s_cbranch_scc0 .LBB0_1096

; #define LAS __attribute__((address_space(3)))
; __device__ __forceinline__ unsigned grab(unsigned* ctr, volatile LAS unsigned* misc, int& it, int tid) {
;     if (tid == 0) misc[20 + (it & 1)] = __hip_atomic_fetch_add(ctr, 1u, __ATOMIC_RELAXED, __HIP_MEMORY_SCOPE_AGENT);
;     __syncthreads();
;     const unsigned v = (unsigned)__builtin_amdgcn_readfirstlane((int)misc[20 + (it & 1)]); ++it; return v;
; }
; __global__ void __launch_bounds__(512, 2) mk_fwd(Args args) {
;     ...
;         while (id < 384u) { attn_sample_g12(args, lds, Qb, Kb, Vb, OG, ML, (int)(id / 3u), (int)(id % 3u), tid); id = grab(fctl + 64 * 20, MISC, it, tid); }
;         {
;             v4u kv[6], vv[6]; AttnU cur = attn_decode(id < 1152u ? (int)id - 384 : 0);
;             if (id < 1152u) attn_load(cur, Kb, Vb, tid, kv, vv);
;             while (id < 1152u) {
.LBB0_1096:
	s_cmp_lg_u32 s99, 0
	s_cbranch_scc1 .Lp4_noswitch
	s_movk_i32 s99, 0x180
	v_readlane_b32 s100, v250, 18
	v_readlane_b32 s101, v250, 19
	s_add_u32 s100, s100, 0x100
	s_addc_u32 s101, s101, 0
	v_writelane_b32 v250, s100, 18
	v_writelane_b32 v250, s101, 19
	v_cmp_eq_u32_e32 vcc, 0, v0
	s_and_saveexec_b64 s[2:3], vcc
	s_cbranch_execz .Lp4_sw1
	v_mov_b32_e32 v2, 0
	v_mov_b32_e32 v3, 1
	global_atomic_add v3, v2, v3, s[100:101] sc0
	v_mov_b32_e32 v2, 0x20074
	s_waitcnt vmcnt(0)
	ds_write_b32 v2, v3
.Lp4_sw1:
	s_or_b64 exec, exec, s[2:3]
	s_waitcnt lgkmcnt(0)
	s_barrier
	v_mov_b32_e32 v2, 0x20074
	ds_read_b32 v2, v2
	s_waitcnt lgkmcnt(0)
	s_nop 0
	v_readfirstlane_b32 s17, v2
	s_add_u32 s17, s17, s99

; __device__ __forceinline__ void attn_load(const AttnU& u, const bf16* Kb, const bf16* Vb, int tid, v4u (&kv)[6], v4u (&vv)[6]) {
; #pragma unroll
;     for (int k = 0; k < 6; ++k) { const int q = tid + 512 * k, s = q >> 3, c = q & 7, i = u.i0 - 128 + s;
;         if (i >= 0) { const size_t off = ((size_t)u.b * 4096 + (size_t)i * u.d + u.r) * 768 + u.hc + 8 * c; kv[k] = *(const v4u*)(Kb + off); vv[k] = *(const v4u*)(Vb + off); }
;         else { kv[k] = (v4u){0u, 0u, 0u, 0u}; vv[k] = (v4u){0u, 0u, 0u, 0u}; } }
; __global__ void __launch_bounds__(512, 2) mk_fwd(Args args) {
;     ...
;                 const unsigned nid = grab(fctl + 64 * 20, MISC, it, tid);
;                 const AttnU nxt = attn_decode(nid < 1152u ? (int)nid - 384 : 0);
;                 if (nid < 1152u) attn_load(nxt, Kb, Vb, tid, kv, vv);
.LBB0_1110:
	s_or_b64 exec, exec, s[0:1]
	s_lshl_b32 s0, s14, 2
	s_add_i32 s0, s0, 0
	s_add_i32 s0, s0, 0x20050
	v_mov_b32_e32 v2, s0
	s_waitcnt lgkmcnt(0)
	s_barrier
	ds_read_b32 v2, v2
	s_waitcnt lgkmcnt(0)
	v_readfirstlane_b32 s17, v2
	s_add_u32 s17, s17, s99
	s_cmpk_gt_u32 s17, 0x47f
	s_cselect_b64 s[90:91], -1, 0
	s_add_i32 s0, s17, 0xfe80
	s_cmpk_lt_u32 s17, 0x480
	s_cselect_b32 s1, s0, 0
	s_sext_i32_i16 s0, s1
	s_mulk_i32 s0, 0x2aab
	s_lshr_b32 s10, s0, 31
	s_ashr_i32 s0, s0, 21
	s_add_i32 s0, s0, s10
	s_bfe_i64 s[10:11], s[0:1], 0x100000
	s_mulk_i32 s0, 0xc0
	s_sub_i32 s0, s1, s0
	s_sext_i32_i16 s1, s0
	s_bfe_u32 s1, s1, 0x60019
	s_add_i32 s1, s0, s1
	s_sext_i32_i16 s12, s1
	s_and_b32 s1, s1, 0xffc0
	s_sub_i32 s0, s0, s1
	s_bfe_i32 s1, s0, 0x80000
	s_and_b32 s1, 0xffff, s1
	s_lshr_b32 s1, s1, 11
	s_and_b32 s1, s1, 15
	s_ashr_i32 s85, s12, 6
	s_add_i32 s1, s0, s1
	s_bfe_i32 s12, s1, 0x80000
	s_and_b32 s1, s1, 0xfff0
	s_lshl_b32 s18, s85, 1
	s_sub_i32 s13, s0, s1
	s_lshr_b32 s14, 16, s18
	s_sext_i32_i8 s0, s13
	v_cvt_f32_ubyte0_e32 v3, s14
	v_cvt_f32_i32_e32 v2, s0
	v_rcp_iflag_f32_e32 v4, v3
	s_sext_i32_i16 s12, s12
	s_ashr_i32 s0, s0, 30
	s_ashr_i32 s19, s12, 4
	v_mul_f32_e32 v4, v2, v4
	v_trunc_f32_e32 v4, v4
	v_fma_f32 v2, -v4, v3, v2
	v_cvt_i32_f32_e32 v4, v4
	s_or_b32 s12, s0, 1
	v_cmp_ge_f32_e64 s[0:1], |v2|, v3
	s_and_b64 s[0:1], s[0:1], exec
	s_cselect_b32 s0, s12, 0
	v_readfirstlane_b32 s1, v4
	s_add_i32 s12, s1, s0
	s_bfe_i64 s[0:1], s[12:13], 0x80000
	s_mul_i32 s12, s12, s14
	s_sub_i32 s14, s13, s12
	s_sext_i32_i8 s12, s14
	s_lshl_b32 s20, s12, 8
	s_lshl_b32 s12, s85, 8
	s_lshl_b32 s13, s19, 6
	s_add_i32 s84, s13, s12
	s_and_b64 vcc, exec, s[90:91]
	s_cbranch_vccnz .LBB0_1126
	v_mov_b32_e32 v94, 0
	v_mov_b32_e32 v95, v91
	v_add_u32_e32 v4, s20, v148
	v_mov_b32_e32 v96, v91
	v_mov_b32_e32 v97, v91
	v_mov_b64_e32 v[86:87], v[94:95]
	v_cmp_lt_i32_e32 vcc, -1, v4
	v_mov_b32_e32 v82, v91
	v_mov_b32_e32 v83, v91
	v_mov_b32_e32 v84, v91
	v_mov_b32_e32 v85, v91
	v_or_b32_e32 v2, s84, v146
	v_mov_b64_e32 v[88:89], v[96:97]
	s_and_saveexec_b64 s[12:13], vcc
	s_cbranch_execz .LBB0_1113
	s_lshl_b64 vcc, s[10:11], 12
	v_mov_b32_e32 v5, v91
	s_add_u32 vcc_lo, vcc_lo, s0
	v_lshlrev_b64 v[4:5], s18, v[4:5]
	s_addc_u32 vcc_hi, vcc_hi, s1
	s_ashr_i32 s15, s84, 31
	v_lshl_add_u64 v[4:5], vcc, 0, v[4:5]
	v_mov_b32_e32 v3, s15
	v_mad_u64_u32 v[6:7], vcc, v4, s16, v[2:3]
	v_mov_b32_e32 v4, v7
	v_mad_u64_u32 v[4:5], vcc, v5, s16, v[4:5]
	v_mov_b32_e32 v7, v4
	v_lshlrev_b64 v[4:5], 1, v[6:7]
	v_lshl_add_u64 v[6:7], s[4:5], 0, v[4:5]
	v_lshl_add_u64 v[4:5], s[88:89], 0, v[4:5]
	global_load_dwordx4 v[86:89], v[6:7], off
	global_load_dwordx4 v[82:85], v[4:5], off

; #define LAS __attribute__((address_space(3)))
; __device__ __forceinline__ unsigned grab(unsigned* ctr, volatile LAS unsigned* misc, int& it, int tid) {
;     if (tid == 0) misc[20 + (it & 1)] = __hip_atomic_fetch_add(ctr, 1u, __ATOMIC_RELAXED, __HIP_MEMORY_SCOPE_AGENT);
;     __syncthreads();
;     const unsigned v = (unsigned)__builtin_amdgcn_readfirstlane((int)misc[20 + (it & 1)]); ++it; return v;
; }
; __global__ void __launch_bounds__(512, 2) mk_fwd(Args args) {
;     ...
;             while (id < 1664u) { conv_unit<32, false>(args, lds, Ub, CONVF, cw, (int)id - 1152, tid); id = grab(fctl + 64 * 20, MISC, it, tid); }
.LBB0_1134:
	s_or_b64 exec, exec, s[0:1]
	s_lshl_b32 s0, s11, 2
	s_add_i32 s0, s0, 0
	s_add_i32 s0, s0, 0x20050
	v_mov_b32_e32 v23, s0
	s_waitcnt lgkmcnt(0)
	s_barrier
	ds_read_b32 v23, v23
	s_add_i32 s33, s33, 1
	s_waitcnt lgkmcnt(0)
	v_readfirstlane_b32 s17, v23
	s_add_u32 s17, s17, s99
	s_cmpk_gt_u32 s17, 0x67f
	s_cbranch_scc1 .LBB0_1200

; #define LAS __attribute__((address_space(3)))
; __device__ __forceinline__ unsigned grab(unsigned* ctr, volatile LAS unsigned* misc, int& it, int tid) {
;     if (tid == 0) misc[20 + (it & 1)] = __hip_atomic_fetch_add(ctr, 1u, __ATOMIC_RELAXED, __HIP_MEMORY_SCOPE_AGENT);
;     __syncthreads();
;     const unsigned v = (unsigned)__builtin_amdgcn_readfirstlane((int)misc[20 + (it & 1)]); ++it; return v;
; }
; __global__ void __launch_bounds__(512, 2) mk_fwd(Args args) {
;     ...
;             while (id < 1792u) { conv_unit<4, true>(args, lds, Ub, CONVF, cw, (int)id - 1664, tid); id = grab(fctl + 64 * 20, MISC, it, tid); }
.LBB0_1203:
	s_or_b64 exec, exec, s[0:1]
	s_lshl_b32 s0, s11, 2
	s_add_i32 s0, s0, 0
	s_add_i32 s0, s0, 0x20050
	v_mov_b32_e32 v17, s0
	s_waitcnt lgkmcnt(0)
	s_barrier
	ds_read_b32 v17, v17
	s_add_i32 s33, s33, 1
	s_waitcnt lgkmcnt(0)
	v_readfirstlane_b32 s17, v17
	s_add_u32 s17, s17, s99
	s_cmpk_lt_u32 s17, 0x700
	s_cbranch_scc0 .LBB0_1209
